# grid barrier: waiting workgroups poll the top-level generation word directly (skip per-XCD republish stage)
# speedup vs baseline: 1.0026x; 1.0023x over previous
; __device__ __forceinline__ unsigned xb_ld(unsigned* p)              { return __hip_atomic_load(p, __ATOMIC_RELAXED, __HIP_MEMORY_SCOPE_AGENT); }
; __device__ __forceinline__ unsigned xb_add(unsigned* p, unsigned v) { return __hip_atomic_fetch_add(p, v, __ATOMIC_RELAXED, __HIP_MEMORY_SCOPE_AGENT); }
; #define XB_SPIN(cond, bar) do { unsigned _sp = 0; while (cond) { __builtin_amdgcn_s_sleep(1); \
;     if ((++_sp & 255u) == 0u) { if (xb_ld(&(bar)[XB_TMO])) break; if (_sp > XB_SPIN_CAP) { atomicAdd(&(bar)[XB_TMO], 1u); break; } } } } while (0)
; __device__ __forceinline__ void xcd_barrier(const XcdBarrier& b) {
;     ...
;             const unsigned og = xb_add(&bar[XB_TOP], 1u);
;             const unsigned tg = og / nx;
;             if (og + 1u == (tg + 1u) * nx) xb_add(&bar[XB_TOPGEN], 1u);
;             else XB_SPIN(xb_ld(&bar[XB_TOPGEN]) == tg, bar);
.LBB0_638:
	global_atomic_add v4, v[194:195], v202, off sc0
	v_cvt_f32_u32_e32 v0, v3
	v_sub_u32_e32 v5, 0, v3
	v_rcp_iflag_f32_e32 v0, v0
	s_nop 0
	v_mul_f32_e32 v0, 0x4f7ffffe, v0
	v_cvt_u32_f32_e32 v0, v0
	v_mul_lo_u32 v5, v5, v0
	v_mul_hi_u32 v5, v0, v5
	v_add_u32_e32 v0, v0, v5
	s_waitcnt vmcnt(0)
	v_mul_hi_u32 v0, v4, v0
	v_mul_lo_u32 v5, v0, v3
	v_sub_u32_e32 v5, v4, v5
	v_add_u32_e32 v6, 1, v0
	v_cmp_ge_u32_e32 vcc, v5, v3
	v_add_u32_e32 v4, 1, v4
	s_nop 0
	v_cndmask_b32_e32 v0, v0, v6, vcc
	v_sub_u32_e32 v6, v5, v3
	v_cndmask_b32_e32 v5, v5, v6, vcc
	v_add_u32_e32 v6, 1, v0
	v_cmp_ge_u32_e32 vcc, v5, v3
	s_nop 1
	v_cndmask_b32_e32 v0, v0, v6, vcc
	v_mul_lo_u32 v5, v3, v0
	v_add_u32_e32 v3, v5, v3
	v_cmp_ne_u32_e32 vcc, v4, v3
	s_and_saveexec_b64 s[2:3], vcc
	s_xor_b64 s[2:3], exec, s[2:3]
	s_cbranch_execz .LBB0_652
	s_waitcnt lgkmcnt(0)
	v_mov_b32_e32 v7, 0x3500
	global_load_dword v2, v7, s[92:93] sc1
	s_waitcnt vmcnt(0)
	v_cmp_eq_u32_e32 vcc, v2, v0
	s_and_saveexec_b64 s[4:5], vcc
	s_cbranch_execz .LBB0_651
	s_mov_b32 s6, 1
	s_mov_b64 s[8:9], 0
	s_branch .LBB0_642

; __device__ __forceinline__ unsigned xb_ld(unsigned* p)              { return __hip_atomic_load(p, __ATOMIC_RELAXED, __HIP_MEMORY_SCOPE_AGENT); }
; #define XB_SPIN(cond, bar) do { unsigned _sp = 0; while (cond) { __builtin_amdgcn_s_sleep(1); \
;     if ((++_sp & 255u) == 0u) { if (xb_ld(&(bar)[XB_TMO])) break; if (_sp > XB_SPIN_CAP) { atomicAdd(&(bar)[XB_TMO], 1u); break; } } } } while (0)
; __device__ __forceinline__ void xcd_barrier(const XcdBarrier& b) {
;     ...
;             else XB_SPIN(xb_ld(&bar[XB_TOPGEN]) == tg, bar);
.LBB0_646:
	global_load_dword v2, v7, s[92:93] sc1
	s_add_i32 s6, s6, 1
	s_mov_b64 s[14:15], -1
	s_waitcnt vmcnt(0)
	v_cmp_ne_u32_e32 vcc, v2, v0
	s_orn2_b64 s[12:13], vcc, exec
	s_branch .LBB0_641
